# k17 + xbar: XCD-hierarchical seam arrive (per-XCC counter via XCC_ID, one L2 write-back per XCC instead of 32, cross-XCC counter polled by all)
# speedup vs baseline: 1.0390x; 1.0390x over previous
; #define PH(k) if (lo <= (k) && (k) < hi) for (int rep_ = 0; rep_ <= ((REP_MASK >> (k)) & 1); ++rep_)
; #define SEAM(k) if (lo <= (k) && (k) + 1 < hi) grid_bar(barctr, (unsigned)((k) + 1 - lo) * gridDim.x, wave)
; __device__ __forceinline__ void grid_bar(unsigned* ctr, unsigned target, int wave) {
;     __builtin_amdgcn_s_waitcnt(0x0F70);
;     __syncthreads();
;     if (wave == 0) {
;         int l; asm volatile("v_mbcnt_lo_u32_b32 %0, -1, 0\n\tv_mbcnt_hi_u32_b32 %0, -1, %0" : "=v"(l));
;         if (l == 0) {
;             __builtin_amdgcn_fence(__ATOMIC_RELEASE, "agent");
;             __hip_atomic_fetch_add(ctr, 1u, __ATOMIC_RELAXED, __HIP_MEMORY_SCOPE_AGENT);
;             while (__hip_atomic_load(ctr, __ATOMIC_RELAXED, __HIP_MEMORY_SCOPE_AGENT) < target) __builtin_amdgcn_s_sleep(2);
;             __builtin_amdgcn_fence(__ATOMIC_ACQUIRE, "agent");
;         }
;     }
;     __syncthreads();
; }
; __global__ void __launch_bounds__(NTHR, 2) fwd_kernel(Params p) {
;     ...
;     PH(0) { phase_prep(p, (float*)smem, wave); } SEAM(0);
.LBB0_138:
	v_readlane_b32 s4, v253, 8
	v_readlane_b32 s6, v253, 10
	v_readlane_b32 s7, v253, 11
	s_add_u32 s0, s6, 0x4000
	s_addc_u32 s1, s7, 0
	v_readlane_b32 s5, v253, 9
	v_writelane_b32 v253, s0, 61
	s_cmp_gt_i32 s73, 1
	s_nop 0
	v_writelane_b32 v253, s1, 62
	s_cselect_b64 s[0:1], -1, 0
	s_and_b64 s[4:5], s[94:95], s[0:1]
	s_andn2_b64 vcc, exec, s[4:5]
	s_cbranch_vccnz .LBB0_148
	s_cmp_gt_u32 s74, 63
	s_waitcnt vmcnt(0)
	s_barrier
	s_cbranch_scc1 .LBB0_147
	v_mbcnt_lo_u32_b32 v0, -1, 0
	v_mbcnt_hi_u32_b32 v0, -1, v0
	s_nop 0
	v_cmp_eq_u32_e32 vcc, 0, v0
	s_and_saveexec_b64 s[4:5], vcc
	s_cbranch_execz .LBB0_146
	s_mov_b64 s[8:9], exec
	v_mbcnt_lo_u32_b32 v0, s8, 0
	v_mbcnt_hi_u32_b32 v0, s9, v0
	v_cmp_eq_u32_e32 vcc, 0, v0
	s_and_saveexec_b64 s[6:7], vcc
	s_cbranch_execz .LBB0_143
	s_cmpk_lg_i32 s93, 0x100
	s_cbranch_scc1 .Lxb9_flat
	s_getreg_b32 s3, hwreg(HW_REG_XCC_ID, 0, 3)
	v_readlane_b32 s8, v253, 61
	v_readlane_b32 s9, v253, 62
	s_lshl_b32 s3, s3, 4
	s_addk_i32 s3, 0x80
	v_mov_b32_e32 v0, s3
	v_mov_b32_e32 v1, 1
	s_nop 4
	global_atomic_add v1, v0, v1, s[8:9] sc0
	s_waitcnt vmcnt(0)
	v_add_u32_e32 v1, 1, v1
	v_and_b32_e32 v1, 31, v1
	v_cmp_ne_u32_e32 vcc, 0, v1
	s_cbranch_vccnz .LBB0_143
	buffer_wbl2 sc1
	s_waitcnt vmcnt(0)
	v_mov_b32_e32 v0, 0
	v_mov_b32_e32 v1, 1
	global_atomic_add v0, v1, s[8:9]
	s_branch .LBB0_143
.Lxb9_flat:
	buffer_wbl2 sc1
	s_bcnt1_i32_b64 s3, s[8:9]
	v_readlane_b32 s8, v253, 61
	v_mov_b32_e32 v0, 0
	v_mov_b32_e32 v1, s3
	v_readlane_b32 s9, v253, 62
	s_nop 4
	global_atomic_add v0, v1, s[8:9]
.LBB0_143:
	s_or_b64 exec, exec, s[6:7]
	v_readlane_b32 s6, v253, 61
	v_mov_b32_e32 v0, 0
	v_readlane_b32 s7, v253, 62
	s_sub_i32 s3, 1, s72
	s_mul_i32 s3, s93, s3
	s_cmpk_lg_i32 s93, 0x100
	s_cbranch_scc1 .Lxb9_p
	s_lshr_b32 s3, s3, 5
.Lxb9_p:
	s_nop 2
	global_load_dword v1, v0, s[6:7] sc1
	s_waitcnt vmcnt(0)
	v_cmp_le_u32_e32 vcc, s3, v1
	s_cbranch_vccnz .LBB0_145

; __device__ __forceinline__ void grid_bar(unsigned* ctr, unsigned target, int wave) {
;     __builtin_amdgcn_s_waitcnt(0x0F70);
;     __syncthreads();
;     if (wave == 0) {
;         int l; asm volatile("v_mbcnt_lo_u32_b32 %0, -1, 0\n\tv_mbcnt_hi_u32_b32 %0, -1, %0" : "=v"(l));
;         if (l == 0) {
;             __builtin_amdgcn_fence(__ATOMIC_RELEASE, "agent");
;             __hip_atomic_fetch_add(ctr, 1u, __ATOMIC_RELAXED, __HIP_MEMORY_SCOPE_AGENT);
;             while (__hip_atomic_load(ctr, __ATOMIC_RELAXED, __HIP_MEMORY_SCOPE_AGENT) < target) __builtin_amdgcn_s_sleep(2);
;             __builtin_amdgcn_fence(__ATOMIC_ACQUIRE, "agent");
;         }
;     }
;     __syncthreads();
; }
.LBB0_157:
	s_cmp_gt_i32 s73, 2
	s_cselect_b64 s[0:1], -1, 0
	s_and_b64 s[4:5], s[6:7], s[0:1]
	s_andn2_b64 vcc, exec, s[4:5]
	s_cbranch_vccnz .LBB0_167
	s_cmp_gt_u32 s74, 63
	s_waitcnt vmcnt(0)
	s_barrier
	s_cbranch_scc1 .LBB0_166
	v_mbcnt_lo_u32_b32 v0, -1, 0
	v_mbcnt_hi_u32_b32 v0, -1, v0
	s_nop 0
	v_cmp_eq_u32_e32 vcc, 0, v0
	s_and_saveexec_b64 s[4:5], vcc
	s_cbranch_execz .LBB0_165
	s_mov_b64 s[8:9], exec
	v_mbcnt_lo_u32_b32 v0, s8, 0
	v_mbcnt_hi_u32_b32 v0, s9, v0
	v_cmp_eq_u32_e32 vcc, 0, v0
	s_and_saveexec_b64 s[6:7], vcc
	s_cbranch_execz .LBB0_162
	s_cmpk_lg_i32 s93, 0x100
	s_cbranch_scc1 .Lxb8_flat
	s_getreg_b32 s3, hwreg(HW_REG_XCC_ID, 0, 3)
	v_readlane_b32 s8, v253, 61
	v_readlane_b32 s9, v253, 62
	s_lshl_b32 s3, s3, 4
	s_addk_i32 s3, 0x80
	v_mov_b32_e32 v0, s3
	v_mov_b32_e32 v1, 1
	s_nop 4
	global_atomic_add v1, v0, v1, s[8:9] sc0
	s_waitcnt vmcnt(0)
	v_add_u32_e32 v1, 1, v1
	v_and_b32_e32 v1, 31, v1
	v_cmp_ne_u32_e32 vcc, 0, v1
	s_cbranch_vccnz .LBB0_162
	buffer_wbl2 sc1
	s_waitcnt vmcnt(0)
	v_mov_b32_e32 v0, 0
	v_mov_b32_e32 v1, 1
	global_atomic_add v0, v1, s[8:9]
	s_branch .LBB0_162

; __device__ __forceinline__ void grid_bar(unsigned* ctr, unsigned target, int wave) {
;     ...
;             __hip_atomic_fetch_add(ctr, 1u, __ATOMIC_RELAXED, __HIP_MEMORY_SCOPE_AGENT);
;             while (__hip_atomic_load(ctr, __ATOMIC_RELAXED, __HIP_MEMORY_SCOPE_AGENT) < target) __builtin_amdgcn_s_sleep(2);
;             __builtin_amdgcn_fence(__ATOMIC_ACQUIRE, "agent");
.LBB0_162:
	s_or_b64 exec, exec, s[6:7]
	v_readlane_b32 s6, v253, 61
	v_mov_b32_e32 v0, 0
	v_readlane_b32 s7, v253, 62
	s_sub_i32 s3, 2, s72
	s_mul_i32 s3, s93, s3
	s_cmpk_lg_i32 s93, 0x100
	s_cbranch_scc1 .Lxb8_p
	s_lshr_b32 s3, s3, 5

; __device__ __forceinline__ void grid_bar(unsigned* ctr, unsigned target, int wave) {
;     __builtin_amdgcn_s_waitcnt(0x0F70);
;     __syncthreads();
;     if (wave == 0) {
;         int l; asm volatile("v_mbcnt_lo_u32_b32 %0, -1, 0\n\tv_mbcnt_hi_u32_b32 %0, -1, %0" : "=v"(l));
;         if (l == 0) {
;             __builtin_amdgcn_fence(__ATOMIC_RELEASE, "agent");
;             __hip_atomic_fetch_add(ctr, 1u, __ATOMIC_RELAXED, __HIP_MEMORY_SCOPE_AGENT);
;             while (__hip_atomic_load(ctr, __ATOMIC_RELAXED, __HIP_MEMORY_SCOPE_AGENT) < target) __builtin_amdgcn_s_sleep(2);
;             __builtin_amdgcn_fence(__ATOMIC_ACQUIRE, "agent");
;         }
;     }
;     __syncthreads();
; }
.LBB0_184:
	s_cmp_lt_i32 s73, 4
	s_cselect_b64 s[6:7], -1, 0
	s_xor_b64 s[4:5], s[4:5], -1
	s_or_b64 s[4:5], s[4:5], s[6:7]
	s_mov_b64 s[0:1], -1
	s_and_b64 vcc, exec, s[4:5]
	s_cbranch_vccnz .LBB0_194
	s_cmp_gt_u32 s74, 63
	s_waitcnt vmcnt(0) lgkmcnt(0)
	s_barrier
	s_cbranch_scc1 .LBB0_193
	v_mbcnt_lo_u32_b32 v0, -1, 0
	v_mbcnt_hi_u32_b32 v0, -1, v0
	s_nop 0
	v_cmp_eq_u32_e32 vcc, 0, v0
	s_and_saveexec_b64 s[4:5], vcc
	s_cbranch_execz .LBB0_192
	s_mov_b64 s[8:9], exec
	v_mbcnt_lo_u32_b32 v0, s8, 0
	v_mbcnt_hi_u32_b32 v0, s9, v0
	v_cmp_eq_u32_e32 vcc, 0, v0
	s_and_saveexec_b64 s[6:7], vcc
	s_cbranch_execz .LBB0_189
	s_cmpk_lg_i32 s93, 0x100
	s_cbranch_scc1 .Lxb7_flat
	s_getreg_b32 s3, hwreg(HW_REG_XCC_ID, 0, 3)
	v_readlane_b32 s8, v253, 61
	v_readlane_b32 s9, v253, 62
	s_lshl_b32 s3, s3, 4
	s_addk_i32 s3, 0x80
	v_mov_b32_e32 v0, s3
	v_mov_b32_e32 v1, 1
	s_nop 4
	global_atomic_add v1, v0, v1, s[8:9] sc0
	s_waitcnt vmcnt(0)
	v_add_u32_e32 v1, 1, v1
	v_and_b32_e32 v1, 31, v1
	v_cmp_ne_u32_e32 vcc, 0, v1
	s_cbranch_vccnz .LBB0_189
	buffer_wbl2 sc1
	s_waitcnt vmcnt(0)
	v_mov_b32_e32 v0, 0
	v_mov_b32_e32 v1, 1
	global_atomic_add v0, v1, s[8:9]
	s_branch .LBB0_189

; __device__ __forceinline__ void grid_bar(unsigned* ctr, unsigned target, int wave) {
;     ...
;             __hip_atomic_fetch_add(ctr, 1u, __ATOMIC_RELAXED, __HIP_MEMORY_SCOPE_AGENT);
;             while (__hip_atomic_load(ctr, __ATOMIC_RELAXED, __HIP_MEMORY_SCOPE_AGENT) < target) __builtin_amdgcn_s_sleep(2);
;             __builtin_amdgcn_fence(__ATOMIC_ACQUIRE, "agent");
.LBB0_189:
	s_or_b64 exec, exec, s[6:7]
	v_readlane_b32 s6, v253, 61
	v_mov_b32_e32 v0, 0
	v_readlane_b32 s7, v253, 62
	s_sub_i32 s3, 3, s72
	s_mul_i32 s3, s93, s3
	s_cmpk_lg_i32 s93, 0x100
	s_cbranch_scc1 .Lxb7_p
	s_lshr_b32 s3, s3, 5

; #define PH(k) if (lo <= (k) && (k) < hi) for (int rep_ = 0; rep_ <= ((REP_MASK >> (k)) & 1); ++rep_)
; #define SEAM(k) if (lo <= (k) && (k) + 1 < hi) grid_bar(barctr, (unsigned)((k) + 1 - lo) * gridDim.x, wave)
; __device__ __forceinline__ void grid_bar(unsigned* ctr, unsigned target, int wave) {
;     __builtin_amdgcn_s_waitcnt(0x0F70);
;     __syncthreads();
;     if (wave == 0) {
;         int l; asm volatile("v_mbcnt_lo_u32_b32 %0, -1, 0\n\tv_mbcnt_hi_u32_b32 %0, -1, %0" : "=v"(l));
;         if (l == 0) {
;             __builtin_amdgcn_fence(__ATOMIC_RELEASE, "agent");
;             __hip_atomic_fetch_add(ctr, 1u, __ATOMIC_RELAXED, __HIP_MEMORY_SCOPE_AGENT);
;             while (__hip_atomic_load(ctr, __ATOMIC_RELAXED, __HIP_MEMORY_SCOPE_AGENT) < target) __builtin_amdgcn_s_sleep(2);
;             __builtin_amdgcn_fence(__ATOMIC_ACQUIRE, "agent");
;         }
;     }
;     __syncthreads();
; }
; __global__ void __launch_bounds__(NTHR, 2) fwd_kernel(Params p) {
;     ...
;     for (int o = 0; o < 2; ++o) { PH(3 + o) { phase_conv(p, o, smem, wave); } SEAM(3 + o); }
.LBB0_700:
	s_andn2_b64 vcc, exec, s[22:23]
	s_cbranch_vccnz .LBB0_198
	s_or_b32 s3, s41, 4
	s_cmp_ge_i32 s3, s73
	s_cbranch_scc1 .LBB0_198
	v_readlane_b32 s0, v254, 4
	v_readlane_b32 s1, v254, 5
	s_andn2_b64 vcc, exec, s[0:1]
	s_waitcnt vmcnt(0) lgkmcnt(0)
	s_barrier
	s_cbranch_vccnz .LBB0_197
	v_mbcnt_lo_u32_b32 v0, -1, 0
	v_mbcnt_hi_u32_b32 v0, -1, v0
	s_nop 0
	v_cmp_eq_u32_e32 vcc, 0, v0
	s_and_saveexec_b64 s[0:1], vcc
	s_cbranch_execz .LBB0_196
	s_mov_b64 s[4:5], exec
	v_mbcnt_lo_u32_b32 v0, s4, 0
	v_mbcnt_hi_u32_b32 v0, s5, v0
	v_cmp_eq_u32_e32 vcc, 0, v0
	s_and_saveexec_b64 s[6:7], vcc
	s_cbranch_execz .LBB0_706
	s_cmpk_lg_i32 s93, 0x100
	s_cbranch_scc1 .Lxbc_flat
	s_getreg_b32 s98, hwreg(HW_REG_XCC_ID, 0, 3)
	v_readlane_b32 s4, v253, 61
	v_readlane_b32 s5, v253, 62
	s_lshl_b32 s98, s98, 4
	s_addk_i32 s98, 0x80
	v_mov_b32_e32 v0, s98
	v_mov_b32_e32 v255, 1
	s_nop 4
	global_atomic_add v255, v0, v255, s[4:5] sc0
	s_waitcnt vmcnt(0)
	v_add_u32_e32 v255, 1, v255
	v_and_b32_e32 v255, 31, v255
	v_cmp_ne_u32_e32 vcc, 0, v255
	s_cbranch_vccnz .LBB0_706
	s_cmp_eq_u32 s41, 0
	s_cbranch_scc1 .Lxbc_nowb
	buffer_wbl2 sc1
	s_waitcnt vmcnt(0)
.Lxbc_nowb:
	v_mov_b32_e32 v0, 1
	global_atomic_add v57, v0, s[4:5]
	s_branch .LBB0_706
.Lxbc_flat:
	s_cmp_eq_u32 s41, 0
	s_cbranch_scc1 .Lseam3_nowb
	buffer_wbl2 sc1
.Lseam3_nowb:
	s_bcnt1_i32_b64 s4, s[4:5]
	v_mov_b32_e32 v0, s4
	v_readlane_b32 s4, v253, 61
	v_readlane_b32 s5, v253, 62
	s_nop 4
	global_atomic_add v57, v0, s[4:5]
.LBB0_706:
	s_or_b64 exec, exec, s[6:7]
	s_cmp_eq_u32 s41, 0
	s_cbranch_scc1 .LBB0_196
	v_readlane_b32 s4, v253, 61
	v_readlane_b32 s5, v253, 62
	s_sub_i32 s3, s3, s72
	s_mul_i32 s3, s3, s93
	s_cmpk_lg_i32 s93, 0x100
	s_cbranch_scc1 .Lxbc_p
	s_lshr_b32 s3, s3, 5
.Lxbc_p:
	s_nop 2
	global_load_dword v0, v57, s[4:5] sc1
	s_waitcnt vmcnt(0)
	v_cmp_le_u32_e32 vcc, s3, v0
	s_cbranch_vccnz .LBB0_195

; __device__ __forceinline__ void grid_bar(unsigned* ctr, unsigned target, int wave) {
;     __builtin_amdgcn_s_waitcnt(0x0F70);
;     __syncthreads();
;     if (wave == 0) {
;         int l; asm volatile("v_mbcnt_lo_u32_b32 %0, -1, 0\n\tv_mbcnt_hi_u32_b32 %0, -1, %0" : "=v"(l));
;         if (l == 0) {
;             __builtin_amdgcn_fence(__ATOMIC_RELEASE, "agent");
;             __hip_atomic_fetch_add(ctr, 1u, __ATOMIC_RELAXED, __HIP_MEMORY_SCOPE_AGENT);
;             while (__hip_atomic_load(ctr, __ATOMIC_RELAXED, __HIP_MEMORY_SCOPE_AGENT) < target) __builtin_amdgcn_s_sleep(2);
;             __builtin_amdgcn_fence(__ATOMIC_ACQUIRE, "agent");
;         }
;     }
;     __syncthreads();
; }
.LBB0_734:
	s_cmp_gt_i32 s73, 6
	s_cselect_b64 s[4:5], -1, 0
	s_and_b64 s[0:1], s[36:37], s[4:5]
	s_andn2_b64 vcc, exec, s[0:1]
	s_cbranch_vccnz .LBB0_744
	v_readlane_b32 s0, v254, 4
	v_readlane_b32 s1, v254, 5
	s_andn2_b64 vcc, exec, s[0:1]
	s_waitcnt vmcnt(0) lgkmcnt(0)
	s_barrier
	s_cbranch_vccnz .LBB0_743
	v_mbcnt_lo_u32_b32 v0, -1, 0
	v_mbcnt_hi_u32_b32 v0, -1, v0
	s_nop 0
	v_cmp_eq_u32_e32 vcc, 0, v0
	s_and_saveexec_b64 s[0:1], vcc
	s_cbranch_execz .LBB0_742
	s_mov_b64 s[8:9], exec
	v_mbcnt_lo_u32_b32 v0, s8, 0
	v_mbcnt_hi_u32_b32 v0, s9, v0
	v_cmp_eq_u32_e32 vcc, 0, v0
	s_and_saveexec_b64 s[6:7], vcc
	s_cbranch_execz .LBB0_739
	s_cmpk_lg_i32 s93, 0x100
	s_cbranch_scc1 .Lxb6_flat
	s_getreg_b32 s3, hwreg(HW_REG_XCC_ID, 0, 3)
	v_readlane_b32 s8, v253, 61
	v_readlane_b32 s9, v253, 62
	s_lshl_b32 s3, s3, 4
	s_addk_i32 s3, 0x80
	v_mov_b32_e32 v0, s3
	v_mov_b32_e32 v1, 1
	s_nop 4
	global_atomic_add v1, v0, v1, s[8:9] sc0
	s_waitcnt vmcnt(0)
	v_add_u32_e32 v1, 1, v1
	v_and_b32_e32 v1, 31, v1
	v_cmp_ne_u32_e32 vcc, 0, v1
	s_cbranch_vccnz .LBB0_739
	buffer_wbl2 sc1
	s_waitcnt vmcnt(0)
	v_mov_b32_e32 v0, 0
	v_mov_b32_e32 v1, 1
	global_atomic_add v0, v1, s[8:9]
	s_branch .LBB0_739

; __device__ __forceinline__ void grid_bar(unsigned* ctr, unsigned target, int wave) {
;     ...
;             __hip_atomic_fetch_add(ctr, 1u, __ATOMIC_RELAXED, __HIP_MEMORY_SCOPE_AGENT);
;             while (__hip_atomic_load(ctr, __ATOMIC_RELAXED, __HIP_MEMORY_SCOPE_AGENT) < target) __builtin_amdgcn_s_sleep(2);
;             __builtin_amdgcn_fence(__ATOMIC_ACQUIRE, "agent");
.LBB0_739:
	s_or_b64 exec, exec, s[6:7]
	v_readlane_b32 s6, v253, 61
	v_mov_b32_e32 v0, 0
	v_readlane_b32 s7, v253, 62
	s_sub_i32 s3, 6, s72
	s_mul_i32 s3, s93, s3
	s_cmpk_lg_i32 s93, 0x100
	s_cbranch_scc1 .Lxb6_p
	s_lshr_b32 s3, s3, 5

; __device__ __forceinline__ void grid_bar(unsigned* ctr, unsigned target, int wave) {
;     __builtin_amdgcn_s_waitcnt(0x0F70);
;     __syncthreads();
;     if (wave == 0) {
;         int l; asm volatile("v_mbcnt_lo_u32_b32 %0, -1, 0\n\tv_mbcnt_hi_u32_b32 %0, -1, %0" : "=v"(l));
;         if (l == 0) {
;             __builtin_amdgcn_fence(__ATOMIC_RELEASE, "agent");
;             __hip_atomic_fetch_add(ctr, 1u, __ATOMIC_RELAXED, __HIP_MEMORY_SCOPE_AGENT);
;             while (__hip_atomic_load(ctr, __ATOMIC_RELAXED, __HIP_MEMORY_SCOPE_AGENT) < target) __builtin_amdgcn_s_sleep(2);
;             __builtin_amdgcn_fence(__ATOMIC_ACQUIRE, "agent");
;         }
;     }
;     __syncthreads();
; }
.LBB0_748:
	s_cmp_gt_i32 s73, 7
	s_cselect_b64 s[6:7], -1, 0
	s_and_b64 s[0:1], s[0:1], s[6:7]
	s_andn2_b64 vcc, exec, s[0:1]
	s_cbranch_vccnz .LBB0_759
	v_readlane_b32 s0, v254, 4
	v_readlane_b32 s1, v254, 5
	s_andn2_b64 vcc, exec, s[0:1]
	s_waitcnt vmcnt(0) lgkmcnt(0)
	s_barrier
	s_cbranch_vccnz .LBB0_758
	v_mbcnt_lo_u32_b32 v0, -1, 0
	v_mbcnt_hi_u32_b32 v0, -1, v0
	s_nop 0
	v_cmp_eq_u32_e32 vcc, 0, v0
	s_and_saveexec_b64 s[0:1], vcc
	s_cbranch_execz .LBB0_757
	s_mov_b64 s[8:9], exec
	v_mbcnt_lo_u32_b32 v0, s8, 0
	v_mbcnt_hi_u32_b32 v0, s9, v0
	v_cmp_eq_u32_e32 vcc, 0, v0
	s_and_saveexec_b64 s[4:5], vcc
	s_cbranch_execz .LBB0_753
	s_cmpk_lg_i32 s93, 0x100
	s_cbranch_scc1 .Lxb5_flat
	s_getreg_b32 s3, hwreg(HW_REG_XCC_ID, 0, 3)
	v_readlane_b32 s8, v253, 61
	v_readlane_b32 s9, v253, 62
	s_lshl_b32 s3, s3, 4
	s_addk_i32 s3, 0x80
	v_mov_b32_e32 v0, s3
	v_mov_b32_e32 v1, 1
	s_nop 4
	global_atomic_add v1, v0, v1, s[8:9] sc0
	s_waitcnt vmcnt(0)
	v_add_u32_e32 v1, 1, v1
	v_and_b32_e32 v1, 31, v1
	v_cmp_ne_u32_e32 vcc, 0, v1
	s_cbranch_vccnz .LBB0_753
	buffer_wbl2 sc1
	s_waitcnt vmcnt(0)
	v_mov_b32_e32 v0, 0
	v_mov_b32_e32 v1, 1
	global_atomic_add v0, v1, s[8:9]
	s_branch .LBB0_753

; __device__ __forceinline__ void grid_bar(unsigned* ctr, unsigned target, int wave) {
;     ...
;             __hip_atomic_fetch_add(ctr, 1u, __ATOMIC_RELAXED, __HIP_MEMORY_SCOPE_AGENT);
;             while (__hip_atomic_load(ctr, __ATOMIC_RELAXED, __HIP_MEMORY_SCOPE_AGENT) < target) __builtin_amdgcn_s_sleep(2);
;             __builtin_amdgcn_fence(__ATOMIC_ACQUIRE, "agent");
.LBB0_753:
	s_or_b64 exec, exec, s[4:5]
	v_readlane_b32 s4, v253, 61
	v_mov_b32_e32 v0, 0
	v_readlane_b32 s5, v253, 62
	s_sub_i32 s3, 7, s72
	s_mul_i32 s3, s93, s3
	s_cmpk_lg_i32 s93, 0x100
	s_cbranch_scc1 .Lxb5_p
	s_lshr_b32 s3, s3, 5
.Lxb5_p:
	s_nop 2
	global_load_dword v1, v0, s[4:5] sc1
	s_waitcnt vmcnt(0)
	v_cmp_le_u32_e32 vcc, s3, v1
	s_cbranch_vccnz .LBB0_756
	v_readlane_b32 s4, v253, 61
	v_readlane_b32 s5, v253, 62

; __device__ __forceinline__ void grid_bar(unsigned* ctr, unsigned target, int wave) {
;     __builtin_amdgcn_s_waitcnt(0x0F70);
;     __syncthreads();
;     if (wave == 0) {
;         int l; asm volatile("v_mbcnt_lo_u32_b32 %0, -1, 0\n\tv_mbcnt_hi_u32_b32 %0, -1, %0" : "=v"(l));
;         if (l == 0) {
;             __builtin_amdgcn_fence(__ATOMIC_RELEASE, "agent");
;             __hip_atomic_fetch_add(ctr, 1u, __ATOMIC_RELAXED, __HIP_MEMORY_SCOPE_AGENT);
;             while (__hip_atomic_load(ctr, __ATOMIC_RELAXED, __HIP_MEMORY_SCOPE_AGENT) < target) __builtin_amdgcn_s_sleep(2);
;             __builtin_amdgcn_fence(__ATOMIC_ACQUIRE, "agent");
;         }
;     }
;     __syncthreads();
; }
.LBB0_772:
	s_cmp_gt_i32 s73, 8
	s_cselect_b64 s[0:1], -1, 0
	s_and_b64 s[4:5], s[4:5], s[0:1]
	s_andn2_b64 vcc, exec, s[4:5]
	s_cbranch_vccnz .LBB0_782
	v_readlane_b32 s4, v254, 4
	v_readlane_b32 s5, v254, 5
	s_andn2_b64 vcc, exec, s[4:5]
	s_waitcnt vmcnt(0) lgkmcnt(0)
	s_barrier
	s_cbranch_vccnz .LBB0_781
	v_mbcnt_lo_u32_b32 v0, -1, 0
	v_mbcnt_hi_u32_b32 v0, -1, v0
	s_nop 0
	v_cmp_eq_u32_e32 vcc, 0, v0
	s_and_saveexec_b64 s[4:5], vcc
	s_cbranch_execz .LBB0_780
	s_mov_b64 s[8:9], exec
	v_mbcnt_lo_u32_b32 v0, s8, 0
	v_mbcnt_hi_u32_b32 v0, s9, v0
	v_cmp_eq_u32_e32 vcc, 0, v0
	s_and_saveexec_b64 s[6:7], vcc
	s_cbranch_execz .LBB0_777
	s_cmpk_lg_i32 s93, 0x100
	s_cbranch_scc1 .Lxb4_flat
	s_getreg_b32 s3, hwreg(HW_REG_XCC_ID, 0, 3)
	v_readlane_b32 s8, v253, 61
	v_readlane_b32 s9, v253, 62
	s_lshl_b32 s3, s3, 4
	s_addk_i32 s3, 0x80
	v_mov_b32_e32 v0, s3
	v_mov_b32_e32 v1, 1
	s_nop 4
	global_atomic_add v1, v0, v1, s[8:9] sc0
	s_waitcnt vmcnt(0)
	v_add_u32_e32 v1, 1, v1
	v_and_b32_e32 v1, 31, v1
	v_cmp_ne_u32_e32 vcc, 0, v1
	s_cbranch_vccnz .LBB0_777
	buffer_wbl2 sc1
	s_waitcnt vmcnt(0)
	v_mov_b32_e32 v0, 0
	v_mov_b32_e32 v1, 1
	global_atomic_add v0, v1, s[8:9]
	s_branch .LBB0_777

; __device__ __forceinline__ void grid_bar(unsigned* ctr, unsigned target, int wave) {
;     ...
;             __hip_atomic_fetch_add(ctr, 1u, __ATOMIC_RELAXED, __HIP_MEMORY_SCOPE_AGENT);
;             while (__hip_atomic_load(ctr, __ATOMIC_RELAXED, __HIP_MEMORY_SCOPE_AGENT) < target) __builtin_amdgcn_s_sleep(2);
;             __builtin_amdgcn_fence(__ATOMIC_ACQUIRE, "agent");
.LBB0_777:
	s_or_b64 exec, exec, s[6:7]
	v_readlane_b32 s6, v253, 61
	v_mov_b32_e32 v0, 0
	v_readlane_b32 s7, v253, 62
	s_sub_i32 s3, 8, s72
	s_mul_i32 s3, s93, s3
	s_cmpk_lg_i32 s93, 0x100
	s_cbranch_scc1 .Lxb4_p
	s_lshr_b32 s3, s3, 5

; __device__ __forceinline__ void grid_bar(unsigned* ctr, unsigned target, int wave) {
;     __builtin_amdgcn_s_waitcnt(0x0F70);
;     __syncthreads();
;     if (wave == 0) {
;         int l; asm volatile("v_mbcnt_lo_u32_b32 %0, -1, 0\n\tv_mbcnt_hi_u32_b32 %0, -1, %0" : "=v"(l));
;         if (l == 0) {
;             __builtin_amdgcn_fence(__ATOMIC_RELEASE, "agent");
;             __hip_atomic_fetch_add(ctr, 1u, __ATOMIC_RELAXED, __HIP_MEMORY_SCOPE_AGENT);
;             while (__hip_atomic_load(ctr, __ATOMIC_RELAXED, __HIP_MEMORY_SCOPE_AGENT) < target) __builtin_amdgcn_s_sleep(2);
;             __builtin_amdgcn_fence(__ATOMIC_ACQUIRE, "agent");
;         }
;     }
;     __syncthreads();
; }
.LBB0_791:
	s_cmp_gt_i32 s73, 9
	s_cselect_b64 s[0:1], -1, 0
	s_and_b64 s[4:5], s[4:5], s[0:1]
	s_andn2_b64 vcc, exec, s[4:5]
	s_cbranch_vccnz .LBB0_801
	v_readlane_b32 s4, v254, 4
	v_readlane_b32 s5, v254, 5
	s_andn2_b64 vcc, exec, s[4:5]
	s_waitcnt vmcnt(0) lgkmcnt(0)
	s_barrier
	s_cbranch_vccnz .LBB0_800
	v_mbcnt_lo_u32_b32 v0, -1, 0
	v_mbcnt_hi_u32_b32 v0, -1, v0
	s_nop 0
	v_cmp_eq_u32_e32 vcc, 0, v0
	s_and_saveexec_b64 s[4:5], vcc
	s_cbranch_execz .LBB0_799
	s_mov_b64 s[8:9], exec
	v_mbcnt_lo_u32_b32 v0, s8, 0
	v_mbcnt_hi_u32_b32 v0, s9, v0
	v_cmp_eq_u32_e32 vcc, 0, v0
	s_and_saveexec_b64 s[6:7], vcc
	s_cbranch_execz .LBB0_796
	s_cmpk_lg_i32 s93, 0x100
	s_cbranch_scc1 .Lxb3_flat
	s_getreg_b32 s3, hwreg(HW_REG_XCC_ID, 0, 3)
	v_readlane_b32 s8, v253, 61
	v_readlane_b32 s9, v253, 62
	s_lshl_b32 s3, s3, 4
	s_addk_i32 s3, 0x80
	v_mov_b32_e32 v0, s3
	v_mov_b32_e32 v1, 1
	s_nop 4
	global_atomic_add v1, v0, v1, s[8:9] sc0
	s_waitcnt vmcnt(0)
	v_add_u32_e32 v1, 1, v1
	v_and_b32_e32 v1, 31, v1
	v_cmp_ne_u32_e32 vcc, 0, v1
	s_cbranch_vccnz .LBB0_796
	buffer_wbl2 sc1
	s_waitcnt vmcnt(0)
	v_mov_b32_e32 v0, 0
	v_mov_b32_e32 v1, 1
	global_atomic_add v0, v1, s[8:9]
	s_branch .LBB0_796

; __device__ __forceinline__ void grid_bar(unsigned* ctr, unsigned target, int wave) {
;     ...
;             __hip_atomic_fetch_add(ctr, 1u, __ATOMIC_RELAXED, __HIP_MEMORY_SCOPE_AGENT);
;             while (__hip_atomic_load(ctr, __ATOMIC_RELAXED, __HIP_MEMORY_SCOPE_AGENT) < target) __builtin_amdgcn_s_sleep(2);
;             __builtin_amdgcn_fence(__ATOMIC_ACQUIRE, "agent");
.LBB0_796:
	s_or_b64 exec, exec, s[6:7]
	v_readlane_b32 s6, v253, 61
	v_mov_b32_e32 v0, 0
	v_readlane_b32 s7, v253, 62
	s_sub_i32 s3, 9, s72
	s_mul_i32 s3, s93, s3
	s_cmpk_lg_i32 s93, 0x100
	s_cbranch_scc1 .Lxb3_p
	s_lshr_b32 s3, s3, 5

; __device__ __forceinline__ void grid_bar(unsigned* ctr, unsigned target, int wave) {
;     __builtin_amdgcn_s_waitcnt(0x0F70);
;     __syncthreads();
;     if (wave == 0) {
;         int l; asm volatile("v_mbcnt_lo_u32_b32 %0, -1, 0\n\tv_mbcnt_hi_u32_b32 %0, -1, %0" : "=v"(l));
;         if (l == 0) {
;             __builtin_amdgcn_fence(__ATOMIC_RELEASE, "agent");
;             __hip_atomic_fetch_add(ctr, 1u, __ATOMIC_RELAXED, __HIP_MEMORY_SCOPE_AGENT);
;             while (__hip_atomic_load(ctr, __ATOMIC_RELAXED, __HIP_MEMORY_SCOPE_AGENT) < target) __builtin_amdgcn_s_sleep(2);
;             __builtin_amdgcn_fence(__ATOMIC_ACQUIRE, "agent");
;         }
;     }
;     __syncthreads();
; }
.LBB0_846:
	s_cmp_gt_i32 s73, 10
	s_cselect_b64 s[0:1], -1, 0
	s_and_b64 s[4:5], s[8:9], s[0:1]
	s_andn2_b64 vcc, exec, s[4:5]
	s_cbranch_vccnz .LBB0_856
	v_readlane_b32 s4, v254, 4
	v_readlane_b32 s5, v254, 5
	s_andn2_b64 vcc, exec, s[4:5]
	s_waitcnt vmcnt(0) lgkmcnt(0)
	s_barrier
	s_cbranch_vccnz .LBB0_855
	v_mbcnt_lo_u32_b32 v0, -1, 0
	v_mbcnt_hi_u32_b32 v0, -1, v0
	s_nop 0
	v_cmp_eq_u32_e32 vcc, 0, v0
	s_and_saveexec_b64 s[4:5], vcc
	s_cbranch_execz .LBB0_854
	s_mov_b64 s[8:9], exec
	v_mbcnt_lo_u32_b32 v0, s8, 0
	v_mbcnt_hi_u32_b32 v0, s9, v0
	v_cmp_eq_u32_e32 vcc, 0, v0
	s_and_saveexec_b64 s[6:7], vcc
	s_cbranch_execz .LBB0_851
	s_cmpk_lg_i32 s93, 0x100
	s_cbranch_scc1 .Lxb2_flat
	s_getreg_b32 s3, hwreg(HW_REG_XCC_ID, 0, 3)
	v_readlane_b32 s8, v253, 61
	v_readlane_b32 s9, v253, 62
	s_lshl_b32 s3, s3, 4
	s_addk_i32 s3, 0x80
	v_mov_b32_e32 v0, s3
	v_mov_b32_e32 v1, 1
	s_nop 4
	global_atomic_add v1, v0, v1, s[8:9] sc0
	s_waitcnt vmcnt(0)
	v_add_u32_e32 v1, 1, v1
	v_and_b32_e32 v1, 31, v1
	v_cmp_ne_u32_e32 vcc, 0, v1
	s_cbranch_vccnz .LBB0_851
	buffer_wbl2 sc1
	s_waitcnt vmcnt(0)
	v_mov_b32_e32 v0, 0
	v_mov_b32_e32 v1, 1
	global_atomic_add v0, v1, s[8:9]
	s_branch .LBB0_851

; __device__ __forceinline__ void grid_bar(unsigned* ctr, unsigned target, int wave) {
;     ...
;             __hip_atomic_fetch_add(ctr, 1u, __ATOMIC_RELAXED, __HIP_MEMORY_SCOPE_AGENT);
;             while (__hip_atomic_load(ctr, __ATOMIC_RELAXED, __HIP_MEMORY_SCOPE_AGENT) < target) __builtin_amdgcn_s_sleep(2);
;             __builtin_amdgcn_fence(__ATOMIC_ACQUIRE, "agent");
.LBB0_851:
	s_or_b64 exec, exec, s[6:7]
	v_readlane_b32 s6, v253, 61
	v_mov_b32_e32 v0, 0
	v_readlane_b32 s7, v253, 62
	s_sub_i32 s3, 10, s72
	s_mul_i32 s3, s93, s3
	s_cmpk_lg_i32 s93, 0x100
	s_cbranch_scc1 .Lxb2_p
	s_lshr_b32 s3, s3, 5

; __device__ __forceinline__ void grid_bar(unsigned* ctr, unsigned target, int wave) {
;     __builtin_amdgcn_s_waitcnt(0x0F70);
;     __syncthreads();
;     if (wave == 0) {
;         int l; asm volatile("v_mbcnt_lo_u32_b32 %0, -1, 0\n\tv_mbcnt_hi_u32_b32 %0, -1, %0" : "=v"(l));
;         if (l == 0) {
;             __builtin_amdgcn_fence(__ATOMIC_RELEASE, "agent");
;             __hip_atomic_fetch_add(ctr, 1u, __ATOMIC_RELAXED, __HIP_MEMORY_SCOPE_AGENT);
;             while (__hip_atomic_load(ctr, __ATOMIC_RELAXED, __HIP_MEMORY_SCOPE_AGENT) < target) __builtin_amdgcn_s_sleep(2);
;             __builtin_amdgcn_fence(__ATOMIC_ACQUIRE, "agent");
;         }
;     }
;     __syncthreads();
; }
.LBB0_867:
	s_cmp_gt_i32 s73, 11
	s_cselect_b64 s[0:1], -1, 0
	s_and_b64 s[4:5], s[4:5], s[0:1]
	s_andn2_b64 vcc, exec, s[4:5]
	s_cbranch_vccnz .LBB0_877
	v_readlane_b32 s4, v254, 4
	v_readlane_b32 s5, v254, 5
	s_andn2_b64 vcc, exec, s[4:5]
	s_waitcnt vmcnt(0) lgkmcnt(0)
	s_barrier
	s_cbranch_vccnz .LBB0_876
	v_mbcnt_lo_u32_b32 v0, -1, 0
	v_mbcnt_hi_u32_b32 v0, -1, v0
	s_nop 0
	v_cmp_eq_u32_e32 vcc, 0, v0
	s_and_saveexec_b64 s[4:5], vcc
	s_cbranch_execz .LBB0_875
	s_mov_b64 s[8:9], exec
	v_mbcnt_lo_u32_b32 v0, s8, 0
	v_mbcnt_hi_u32_b32 v0, s9, v0
	v_cmp_eq_u32_e32 vcc, 0, v0
	s_and_saveexec_b64 s[6:7], vcc
	s_cbranch_execz .LBB0_872
	s_cmpk_lg_i32 s93, 0x100
	s_cbranch_scc1 .Lxb1_flat
	s_getreg_b32 s3, hwreg(HW_REG_XCC_ID, 0, 3)
	v_readlane_b32 s8, v253, 61
	v_readlane_b32 s9, v253, 62
	s_lshl_b32 s3, s3, 4
	s_addk_i32 s3, 0x80
	v_mov_b32_e32 v0, s3
	v_mov_b32_e32 v1, 1
	s_nop 4
	global_atomic_add v1, v0, v1, s[8:9] sc0
	s_waitcnt vmcnt(0)
	v_add_u32_e32 v1, 1, v1
	v_and_b32_e32 v1, 31, v1
	v_cmp_ne_u32_e32 vcc, 0, v1
	s_cbranch_vccnz .LBB0_872
	buffer_wbl2 sc1
	s_waitcnt vmcnt(0)
	v_mov_b32_e32 v0, 0
	v_mov_b32_e32 v1, 1
	global_atomic_add v0, v1, s[8:9]
	s_branch .LBB0_872

; __device__ __forceinline__ void grid_bar(unsigned* ctr, unsigned target, int wave) {
;     ...
;             __hip_atomic_fetch_add(ctr, 1u, __ATOMIC_RELAXED, __HIP_MEMORY_SCOPE_AGENT);
;             while (__hip_atomic_load(ctr, __ATOMIC_RELAXED, __HIP_MEMORY_SCOPE_AGENT) < target) __builtin_amdgcn_s_sleep(2);
;             __builtin_amdgcn_fence(__ATOMIC_ACQUIRE, "agent");
.LBB0_872:
	s_or_b64 exec, exec, s[6:7]
	v_readlane_b32 s6, v253, 61
	v_mov_b32_e32 v0, 0
	v_readlane_b32 s7, v253, 62
	s_sub_i32 s3, 11, s72
	s_mul_i32 s3, s93, s3
	s_cmpk_lg_i32 s93, 0x100
	s_cbranch_scc1 .Lxb1_p
	s_lshr_b32 s3, s3, 5

; __device__ __forceinline__ void grid_bar(unsigned* ctr, unsigned target, int wave) {
;     __builtin_amdgcn_s_waitcnt(0x0F70);
;     __syncthreads();
;     if (wave == 0) {
;         int l; asm volatile("v_mbcnt_lo_u32_b32 %0, -1, 0\n\tv_mbcnt_hi_u32_b32 %0, -1, %0" : "=v"(l));
;         if (l == 0) {
;             __builtin_amdgcn_fence(__ATOMIC_RELEASE, "agent");
;             __hip_atomic_fetch_add(ctr, 1u, __ATOMIC_RELAXED, __HIP_MEMORY_SCOPE_AGENT);
;             while (__hip_atomic_load(ctr, __ATOMIC_RELAXED, __HIP_MEMORY_SCOPE_AGENT) < target) __builtin_amdgcn_s_sleep(2);
;             __builtin_amdgcn_fence(__ATOMIC_ACQUIRE, "agent");
;         }
;     }
;     __syncthreads();
; }
.LBB0_894:
	s_cmp_gt_i32 s73, 12
	s_cselect_b64 s[0:1], -1, 0
	s_and_b64 s[4:5], s[8:9], s[0:1]
	s_andn2_b64 vcc, exec, s[4:5]
	s_cbranch_vccnz .LBB0_904
	v_readlane_b32 s4, v254, 4
	v_readlane_b32 s5, v254, 5
	s_andn2_b64 vcc, exec, s[4:5]
	s_waitcnt vmcnt(0) lgkmcnt(0)
	s_barrier
	s_cbranch_vccnz .LBB0_903
	v_mbcnt_lo_u32_b32 v0, -1, 0
	v_mbcnt_hi_u32_b32 v0, -1, v0
	s_nop 0
	v_cmp_eq_u32_e32 vcc, 0, v0
	s_and_saveexec_b64 s[4:5], vcc
	s_cbranch_execz .LBB0_902
	s_mov_b64 s[8:9], exec
	v_mbcnt_lo_u32_b32 v0, s8, 0
	v_mbcnt_hi_u32_b32 v0, s9, v0
	v_cmp_eq_u32_e32 vcc, 0, v0
	s_and_saveexec_b64 s[6:7], vcc
	s_cbranch_execz .LBB0_899
	s_cmpk_lg_i32 s93, 0x100
	s_cbranch_scc1 .Lxb0_flat
	s_getreg_b32 s3, hwreg(HW_REG_XCC_ID, 0, 3)
	v_readlane_b32 s8, v253, 61
	v_readlane_b32 s9, v253, 62
	s_lshl_b32 s3, s3, 4
	s_addk_i32 s3, 0x80
	v_mov_b32_e32 v0, s3
	v_mov_b32_e32 v1, 1
	s_nop 4
	global_atomic_add v1, v0, v1, s[8:9] sc0
	s_waitcnt vmcnt(0)
	v_add_u32_e32 v1, 1, v1
	v_and_b32_e32 v1, 31, v1
	v_cmp_ne_u32_e32 vcc, 0, v1
	s_cbranch_vccnz .LBB0_899
	buffer_wbl2 sc1
	s_waitcnt vmcnt(0)
	v_mov_b32_e32 v0, 0
	v_mov_b32_e32 v1, 1
	global_atomic_add v0, v1, s[8:9]
	s_branch .LBB0_899

; __device__ __forceinline__ void grid_bar(unsigned* ctr, unsigned target, int wave) {
;     ...
;             __hip_atomic_fetch_add(ctr, 1u, __ATOMIC_RELAXED, __HIP_MEMORY_SCOPE_AGENT);
;             while (__hip_atomic_load(ctr, __ATOMIC_RELAXED, __HIP_MEMORY_SCOPE_AGENT) < target) __builtin_amdgcn_s_sleep(2);
;             __builtin_amdgcn_fence(__ATOMIC_ACQUIRE, "agent");
.LBB0_899:
	s_or_b64 exec, exec, s[6:7]
	v_readlane_b32 s6, v253, 61
	v_mov_b32_e32 v0, 0
	v_readlane_b32 s7, v253, 62
	s_sub_i32 s3, 12, s72
	s_mul_i32 s3, s93, s3
	s_cmpk_lg_i32 s93, 0x100
	s_cbranch_scc1 .Lxb0_p
	s_lshr_b32 s3, s3, 5
